# attention softmax: packed f32 mul/add (144 sites) rewritten as plain f32 pairs
# speedup vs baseline: 1.0068x; 1.0068x over previous
.LBB0_1055:
	v_add3_u32 v83, s18, v186, v188
	ds_read_b128 v[84:87], v83
	ds_read_b128 v[92:95], v83 offset:64
	s_waitcnt lgkmcnt(1)
	v_mfma_f32_16x16x32_bf16 v[88:91], v[84:87], v[0:3], 0
	ds_read_b128 v[98:101], v83 offset:3392
	ds_read_b128 v[102:105], v83 offset:6720
	ds_read_b128 v[156:159], v83 offset:10048
	v_mfma_f32_16x16x32_bf16 v[84:87], v[84:87], v[12:15], 0
	s_waitcnt lgkmcnt(3)
	v_mfma_f32_16x16x32_bf16 v[88:91], v[92:95], v[4:7], v[88:91]
	v_mfma_f32_16x16x32_bf16 v[84:87], v[92:95], v[16:19], v[84:87]
	ds_read_b128 v[92:95], v83 offset:128
	s_waitcnt lgkmcnt(0)
	v_mfma_f32_16x16x32_bf16 v[160:163], v[92:95], v[8:11], v[88:91]
	v_mfma_f32_16x16x32_bf16 v[90:93], v[92:95], v[20:23], v[84:87]
	s_nop 3
	ds_read_b128 v[84:87], v83 offset:3328
	s_waitcnt lgkmcnt(0)
	v_mfma_f32_16x16x32_bf16 v[94:97], v[84:87], v[0:3], 0
	s_nop 0
	v_max_f32_e32 v153, v91, v91
	v_mfma_f32_16x16x32_bf16 v[84:87], v[84:87], v[12:15], 0
	v_mfma_f32_16x16x32_bf16 v[94:97], v[98:101], v[4:7], v[94:97]
	v_mfma_f32_16x16x32_bf16 v[84:87], v[98:101], v[16:19], v[84:87]
	ds_read_b128 v[98:101], v83 offset:3456
	s_waitcnt lgkmcnt(0)
	v_mfma_f32_16x16x32_bf16 v[166:169], v[98:101], v[8:11], v[94:97]
	v_mfma_f32_16x16x32_bf16 v[94:97], v[98:101], v[20:23], v[84:87]
	s_nop 3
	ds_read_b128 v[84:87], v83 offset:6656
	s_waitcnt lgkmcnt(0)
	v_mfma_f32_16x16x32_bf16 v[98:101], v[84:87], v[0:3], 0
	v_mfma_f32_16x16x32_bf16 v[84:87], v[84:87], v[12:15], 0
	v_mfma_f32_16x16x32_bf16 v[98:101], v[102:105], v[4:7], v[98:101]
	v_mfma_f32_16x16x32_bf16 v[84:87], v[102:105], v[16:19], v[84:87]
	ds_read_b128 v[102:105], v83 offset:6784
	s_waitcnt lgkmcnt(0)
	v_mfma_f32_16x16x32_bf16 v[174:177], v[102:105], v[8:11], v[98:101]
	v_mfma_f32_16x16x32_bf16 v[98:101], v[102:105], v[20:23], v[84:87]
	s_nop 3
	ds_read_b128 v[84:87], v83 offset:9984
	s_waitcnt lgkmcnt(0)
	v_mfma_f32_16x16x32_bf16 v[102:105], v[84:87], v[0:3], 0
	v_mfma_f32_16x16x32_bf16 v[84:87], v[84:87], v[12:15], 0
	v_mfma_f32_16x16x32_bf16 v[102:105], v[156:159], v[4:7], v[102:105]
	v_mfma_f32_16x16x32_bf16 v[84:87], v[156:159], v[16:19], v[84:87]
	ds_read_b128 v[156:159], v83 offset:10112
	v_max_f32_e32 v83, v161, v161
	s_waitcnt lgkmcnt(0)
	v_mfma_f32_16x16x32_bf16 v[192:195], v[156:159], v[8:11], v[102:105]
	v_mfma_f32_16x16x32_bf16 v[102:105], v[156:159], v[20:23], v[84:87]
	v_max_f32_e32 v157, v90, v90
	v_max_f32_e32 v153, v157, v153
	v_max_f32_e32 v157, v93, v93
	v_max_f32_e32 v84, v160, v160
	v_max_f32_e32 v83, v84, v83
	v_max_f32_e32 v84, v163, v163
	v_max_f32_e32 v85, v162, v162
	v_max_f32_e32 v84, v85, v84
	v_max_f32_e32 v85, v169, v169
	v_max_f32_e32 v86, v168, v168
	v_max_f32_e32 v85, v86, v85
	v_max3_f32 v85, v166, v167, v85
	v_max3_f32 v83, v83, v84, v85
	v_max_f32_e32 v84, v177, v177
	v_max_f32_e32 v85, v176, v176
	v_max_f32_e32 v84, v85, v84
	v_max_f32_e32 v85, v195, v195
	v_max_f32_e32 v86, v194, v194
	v_max_f32_e32 v85, v86, v85
	v_max3_f32 v84, v174, v175, v84
	v_max3_f32 v85, v192, v193, v85
	v_max3_f32 v83, v83, v84, v85
	s_waitcnt lgkmcnt(0)
	v_max_f32_e32 v84, v84, v84
	v_mov_b32_e32 v84, v83
	s_nop 1
	v_permlane16_swap_b32_e32 v83, v84
	v_max_f32_e32 v83, v83, v84
	v_mov_b32_e32 v84, v83
	s_nop 1
	v_permlane32_swap_b32_e32 v83, v84
	v_max3_f32 v143, v82, v83, v84
	v_sub_f32_e32 v82, v82, v143
	v_exp_f32_e32 v158, v82
	v_sub_f32_e32 v82, v160, v143
	v_exp_f32_e32 v152, v82
	v_sub_f32_e32 v82, v161, v143
	v_exp_f32_e32 v156, v82
	v_sub_f32_e32 v82, v162, v143
	v_exp_f32_e32 v160, v82
	v_sub_f32_e32 v82, v163, v143
	v_exp_f32_e32 v162, v82
	v_sub_f32_e32 v82, v166, v143
	v_exp_f32_e32 v164, v82
	v_sub_f32_e32 v82, v167, v143
	v_exp_f32_e32 v166, v82
	v_sub_f32_e32 v82, v168, v143
	v_exp_f32_e32 v168, v82
	v_sub_f32_e32 v82, v169, v143
	v_exp_f32_e32 v170, v82
	v_sub_f32_e32 v82, v174, v143
	v_exp_f32_e32 v172, v82
	v_sub_f32_e32 v82, v175, v143
	v_exp_f32_e32 v174, v82
	v_sub_f32_e32 v82, v176, v143
	v_exp_f32_e32 v176, v82
	v_sub_f32_e32 v82, v177, v143
	v_exp_f32_e32 v178, v82
	v_sub_f32_e32 v82, v192, v143
	v_exp_f32_e32 v180, v82
	v_sub_f32_e32 v82, v193, v143
	v_exp_f32_e32 v182, v82
	v_sub_f32_e32 v82, v194, v143
	v_exp_f32_e32 v192, v82
	v_sub_f32_e32 v82, v195, v143
	v_exp_f32_e32 v194, v82
	v_mul_f32_e32 v84, v68, v158
	v_mul_f32_e32 v85, v69, v158
	v_mul_f32_e32 v82, v66, v158
	v_mul_f32_e32 v83, v67, v158
	v_mul_f32_e32 v88, v72, v158
	v_mul_f32_e32 v89, v73, v158
	v_mul_f32_e32 v86, v70, v158
	v_mul_f32_e32 v87, v71, v158
	v_mul_f32_e32 v76, v76, v158
	v_mul_f32_e32 v77, v77, v158
	v_mul_f32_e32 v74, v74, v158
	v_mul_f32_e32 v75, v75, v158
	v_mul_f32_e32 v68, v80, v158
	v_mul_f32_e32 v69, v81, v158
	v_mul_f32_e32 v66, v78, v158
	v_mul_f32_e32 v67, v79, v158
	v_max_f32_e32 v159, v92, v92
	v_max_f32_e32 v157, v159, v157
	v_max_f32_e32 v159, v97, v97
	v_max_f32_e32 v161, v96, v96
	v_max_f32_e32 v159, v161, v159
	v_max3_f32 v159, v94, v95, v159
	v_max3_f32 v153, v153, v157, v159
	v_max_f32_e32 v157, v101, v101
	v_max_f32_e32 v159, v100, v100
	v_max_f32_e32 v157, v159, v157
	v_max_f32_e32 v159, v105, v105
	v_max_f32_e32 v161, v104, v104
	v_max_f32_e32 v159, v161, v159
	v_max3_f32 v157, v98, v99, v157
	v_max3_f32 v159, v102, v103, v159
	v_max3_f32 v153, v153, v157, v159
	v_cvt_pk_bf16_f32 v70, v152, v156
	v_cvt_pk_bf16_f32 v71, v160, v162
	v_cvt_pk_bf16_f32 v72, v164, v166
	v_cvt_pk_bf16_f32 v73, v168, v170
	s_waitcnt lgkmcnt(0)
	v_max_f32_e32 v157, v157, v157
	v_mov_b32_e32 v157, v153
	s_nop 1
	v_permlane16_swap_b32_e32 v153, v157
	v_max_f32_e32 v153, v153, v157
	v_mov_b32_e32 v157, v153
	s_nop 1
	v_permlane32_swap_b32_e32 v153, v157
	v_max3_f32 v191, v127, v153, v157
	v_sub_f32_e32 v90, v90, v191
	v_exp_f32_e32 v153, v90
	v_sub_f32_e32 v90, v91, v191
	v_exp_f32_e32 v157, v90
	v_sub_f32_e32 v90, v92, v191
	v_exp_f32_e32 v161, v90
	v_sub_f32_e32 v90, v93, v191
	v_exp_f32_e32 v163, v90
	v_sub_f32_e32 v90, v94, v191
	v_exp_f32_e32 v165, v90
	v_sub_f32_e32 v90, v95, v191
	v_exp_f32_e32 v167, v90
	v_add_f32_e32 v90, 0, v152
	v_add_f32_e32 v91, 0, v153
	v_sub_f32_e32 v92, v96, v191
	v_add_f32_e32 v90, v156, v90
	v_add_f32_e32 v91, v157, v91
	v_exp_f32_e32 v169, v92
	v_add_f32_e32 v90, v160, v90
	v_add_f32_e32 v91, v161, v91
	v_sub_f32_e32 v92, v97, v191
	v_add_f32_e32 v90, v162, v90
	v_add_f32_e32 v91, v163, v91
	v_exp_f32_e32 v171, v92
	v_sub_f32_e32 v92, v98, v191
	v_add_f32_e32 v90, v164, v90
	v_add_f32_e32 v91, v165, v91
	v_exp_f32_e32 v173, v92
	v_sub_f32_e32 v92, v99, v191
	v_add_f32_e32 v90, v166, v90
	v_add_f32_e32 v91, v167, v91
	v_exp_f32_e32 v175, v92
	v_sub_f32_e32 v92, v100, v191
	v_exp_f32_e32 v177, v92
	v_sub_f32_e32 v92, v101, v191
	v_add_f32_e32 v90, v168, v90
	v_add_f32_e32 v91, v169, v91
	v_exp_f32_e32 v179, v92
	v_sub_f32_e32 v92, v102, v191
	v_add_f32_e32 v90, v170, v90
	v_add_f32_e32 v91, v171, v91
	v_exp_f32_e32 v181, v92
	v_sub_f32_e32 v92, v103, v191
	v_add_f32_e32 v90, v172, v90
	v_add_f32_e32 v91, v173, v91
	v_exp_f32_e32 v183, v92
	v_sub_f32_e32 v92, v104, v191
	v_add_f32_e32 v90, v174, v90
	v_add_f32_e32 v91, v175, v91
	v_sub_f32_e32 v127, v127, v191
	v_exp_f32_e32 v193, v92
	v_sub_f32_e32 v92, v105, v191
	v_add_f32_e32 v90, v176, v90
	v_add_f32_e32 v91, v177, v91
	v_exp_f32_e32 v159, v127
	v_exp_f32_e32 v195, v92
	v_add_f32_e32 v90, v178, v90
	v_add_f32_e32 v91, v179, v91
	v_cvt_pk_bf16_f32 v78, v172, v174
	v_add_f32_e32 v90, v180, v90
	v_add_f32_e32 v91, v181, v91
	v_mov_b32_e32 v98, v159
	v_add_f32_e32 v90, v182, v90
	v_add_f32_e32 v91, v183, v91
	v_mul_f32_e32 v92, v52, v98
	v_mul_f32_e32 v93, v53, v98
	v_add_f32_e32 v90, v192, v90
	v_add_f32_e32 v91, v193, v91
	v_mul_f32_e32 v96, v56, v98
	v_mul_f32_e32 v97, v57, v98
	v_add_f32_e32 v90, v194, v90
	v_add_f32_e32 v91, v195, v91
	v_mul_f32_e32 v94, v54, v98
	v_mul_f32_e32 v95, v55, v98
	v_pk_fma_f32 v[150:151], v[150:151], v[158:159], v[90:91]
	v_mul_f32_e32 v90, v50, v98
	v_mul_f32_e32 v91, v51, v98
	v_mul_f32_e32 v60, v60, v98
	v_mul_f32_e32 v61, v61, v98
	v_mul_f32_e32 v58, v58, v98
	v_mul_f32_e32 v59, v59, v98
	v_mul_f32_e32 v52, v64, v98
	v_mul_f32_e32 v53, v65, v98
	v_mul_f32_e32 v50, v62, v98
	v_mul_f32_e32 v51, v63, v98
	v_lshlrev_b32_e32 v98, 1, v187
	v_add3_u32 v127, s18, v98, v189
	ds_read_b64_tr_b16 v[100:101], v127 offset:15872
	ds_read_b64_tr_b16 v[98:99], v127 offset:13312
	ds_read_b64_tr_b16 v[102:103], v127 offset:13320
	v_cvt_pk_bf16_f32 v54, v153, v157
	v_cvt_pk_bf16_f32 v55, v161, v163
	v_cvt_pk_bf16_f32 v56, v165, v167
	v_cvt_pk_bf16_f32 v57, v169, v171
	s_waitcnt lgkmcnt(1)
	v_mfma_f32_16x16x32_bf16 v[82:85], v[98:101], v[70:73], v[82:85]
	ds_read_b64_tr_b16 v[104:105], v127 offset:15880
	v_cvt_pk_bf16_f32 v79, v176, v178
	v_cvt_pk_bf16_f32 v80, v180, v182
	v_mfma_f32_16x16x32_bf16 v[90:93], v[98:101], v[54:57], v[90:93]
	ds_read_b64_tr_b16 v[98:99], v127 offset:13376
	ds_read_b64_tr_b16 v[100:101], v127 offset:15936
	v_cvt_pk_bf16_f32 v81, v192, v194
	v_cvt_pk_bf16_f32 v62, v173, v175
	s_waitcnt lgkmcnt(0)
	v_mfma_f32_16x16x32_bf16 v[74:77], v[98:101], v[70:73], v[74:77]
	v_cvt_pk_bf16_f32 v63, v177, v179
	v_cvt_pk_bf16_f32 v64, v181, v183
	v_cvt_pk_bf16_f32 v65, v193, v195
	v_mfma_f32_16x16x32_bf16 v[58:61], v[98:101], v[54:57], v[58:61]
	ds_read_b64_tr_b16 v[98:99], v127 offset:13384
	ds_read_b64_tr_b16 v[100:101], v127 offset:15944
	v_mfma_f32_16x16x32_bf16 v[86:89], v[102:105], v[70:73], v[86:89]
	v_mfma_f32_16x16x32_bf16 v[94:97], v[102:105], v[54:57], v[94:97]
	s_waitcnt lgkmcnt(0)
	v_mfma_f32_16x16x32_bf16 v[102:105], v[98:101], v[70:73], v[66:69]
	v_mfma_f32_16x16x32_bf16 v[98:101], v[98:101], v[54:57], v[50:53]
	s_nop 2
	ds_read_b64_tr_b16 v[50:51], v127 offset:18432
	ds_read_b64_tr_b16 v[52:53], v127 offset:20992
	ds_read_b64_tr_b16 v[54:55], v127 offset:18440
	ds_read_b64_tr_b16 v[56:57], v127 offset:21000
	s_waitcnt lgkmcnt(2)
	v_mfma_f32_16x16x32_bf16 v[66:69], v[50:53], v[78:81], v[82:85]
	s_nop 2
	ds_read_b64_tr_b16 v[82:83], v127 offset:18496
	ds_read_b64_tr_b16 v[84:85], v127 offset:21056
	s_waitcnt lgkmcnt(0)
	v_mfma_f32_16x16x32_bf16 v[74:77], v[82:85], v[78:81], v[74:77]
	v_mfma_f32_16x16x32_bf16 v[58:61], v[82:85], v[62:65], v[58:61]
	ds_read_b64_tr_b16 v[82:83], v127 offset:18504
	ds_read_b64_tr_b16 v[84:85], v127 offset:21064
	v_mov_b32_e32 v127, v191
	v_mfma_f32_16x16x32_bf16 v[50:53], v[50:53], v[62:65], v[90:93]
	v_mfma_f32_16x16x32_bf16 v[70:73], v[54:57], v[78:81], v[86:89]
	v_mfma_f32_16x16x32_bf16 v[54:57], v[54:57], v[62:65], v[94:97]
	s_waitcnt lgkmcnt(0)
	v_mfma_f32_16x16x32_bf16 v[78:81], v[82:85], v[78:81], v[102:105]
	v_mfma_f32_16x16x32_bf16 v[62:65], v[82:85], v[62:65], v[98:101]
	v_mov_b32_e32 v82, v143
	s_add_i32 s6, s48, -2
	s_cmp_ge_i32 s6, s47
	s_cbranch_scc1 .LBB0_1042
.LBB0_1056:
	s_and_b32 s6, s6, 3
	s_mulk_i32 s6, 0x5c00
	s_add_i32 s18, s6, 0
	v_add3_u32 v83, s18, v186, v188
	ds_read_b128 v[84:87], v83
	ds_read_b128 v[92:95], v83 offset:64
	s_waitcnt lgkmcnt(1)
	v_mfma_f32_16x16x32_bf16 v[88:91], v[84:87], v[0:3], 0
	ds_read_b128 v[98:101], v83 offset:3392
	ds_read_b128 v[102:105], v83 offset:6720
	ds_read_b128 v[156:159], v83 offset:10048
	v_mfma_f32_16x16x32_bf16 v[84:87], v[84:87], v[12:15], 0
	s_waitcnt lgkmcnt(3)
	v_mfma_f32_16x16x32_bf16 v[88:91], v[92:95], v[4:7], v[88:91]
	v_mfma_f32_16x16x32_bf16 v[84:87], v[92:95], v[16:19], v[84:87]
	ds_read_b128 v[92:95], v83 offset:128
	s_waitcnt lgkmcnt(0)
	v_mfma_f32_16x16x32_bf16 v[160:163], v[92:95], v[8:11], v[88:91]
	v_mfma_f32_16x16x32_bf16 v[90:93], v[92:95], v[20:23], v[84:87]
	s_nop 3
	ds_read_b128 v[84:87], v83 offset:3328
	s_waitcnt lgkmcnt(0)
	v_mfma_f32_16x16x32_bf16 v[94:97], v[84:87], v[0:3], 0
	s_nop 0
	v_max_f32_e32 v153, v91, v91
	v_mfma_f32_16x16x32_bf16 v[84:87], v[84:87], v[12:15], 0
	v_mfma_f32_16x16x32_bf16 v[94:97], v[98:101], v[4:7], v[94:97]
	v_mfma_f32_16x16x32_bf16 v[84:87], v[98:101], v[16:19], v[84:87]
	ds_read_b128 v[98:101], v83 offset:3456
	s_waitcnt lgkmcnt(0)
	v_mfma_f32_16x16x32_bf16 v[166:169], v[98:101], v[8:11], v[94:97]
	v_mfma_f32_16x16x32_bf16 v[94:97], v[98:101], v[20:23], v[84:87]
	s_nop 3
	ds_read_b128 v[84:87], v83 offset:6656
	s_waitcnt lgkmcnt(0)
	v_mfma_f32_16x16x32_bf16 v[98:101], v[84:87], v[0:3], 0
	v_mfma_f32_16x16x32_bf16 v[84:87], v[84:87], v[12:15], 0
	v_mfma_f32_16x16x32_bf16 v[98:101], v[102:105], v[4:7], v[98:101]
	v_mfma_f32_16x16x32_bf16 v[84:87], v[102:105], v[16:19], v[84:87]
	ds_read_b128 v[102:105], v83 offset:6784
	s_waitcnt lgkmcnt(0)
	v_mfma_f32_16x16x32_bf16 v[174:177], v[102:105], v[8:11], v[98:101]
	v_mfma_f32_16x16x32_bf16 v[98:101], v[102:105], v[20:23], v[84:87]
	s_nop 3
	ds_read_b128 v[84:87], v83 offset:9984
	s_waitcnt lgkmcnt(0)
	v_mfma_f32_16x16x32_bf16 v[102:105], v[84:87], v[0:3], 0
	v_mfma_f32_16x16x32_bf16 v[84:87], v[84:87], v[12:15], 0
	v_mfma_f32_16x16x32_bf16 v[102:105], v[156:159], v[4:7], v[102:105]
	v_mfma_f32_16x16x32_bf16 v[84:87], v[156:159], v[16:19], v[84:87]
	ds_read_b128 v[156:159], v83 offset:10112
	v_max_f32_e32 v83, v161, v161
	s_waitcnt lgkmcnt(0)
	v_mfma_f32_16x16x32_bf16 v[180:183], v[156:159], v[8:11], v[102:105]
	v_mfma_f32_16x16x32_bf16 v[102:105], v[156:159], v[20:23], v[84:87]
	v_max_f32_e32 v157, v90, v90
	v_max_f32_e32 v153, v157, v153
	v_max_f32_e32 v157, v93, v93
	v_max_f32_e32 v84, v160, v160
	v_max_f32_e32 v83, v84, v83
	v_max_f32_e32 v84, v163, v163
	v_max_f32_e32 v85, v162, v162
	v_max_f32_e32 v84, v85, v84
	v_max_f32_e32 v85, v169, v169
	v_max_f32_e32 v86, v168, v168
	v_max_f32_e32 v85, v86, v85
	v_max3_f32 v85, v166, v167, v85
	v_max3_f32 v83, v83, v84, v85
	v_max_f32_e32 v84, v177, v177
	v_max_f32_e32 v85, v176, v176
	v_max_f32_e32 v84, v85, v84
	v_max_f32_e32 v85, v183, v183
	v_max_f32_e32 v86, v182, v182
	v_max_f32_e32 v85, v86, v85
	v_max3_f32 v84, v174, v175, v84
	v_max3_f32 v85, v180, v181, v85
	v_max3_f32 v83, v83, v84, v85
	s_waitcnt lgkmcnt(0)
	v_max_f32_e32 v84, v84, v84
	v_mov_b32_e32 v84, v83
	s_nop 1
	v_permlane16_swap_b32_e32 v83, v84
	v_max_f32_e32 v83, v83, v84
	v_mov_b32_e32 v84, v83
	s_nop 1
	v_permlane32_swap_b32_e32 v83, v84
	v_max3_f32 v143, v82, v83, v84
	v_sub_f32_e32 v82, v82, v143
	v_exp_f32_e32 v158, v82
	v_sub_f32_e32 v82, v160, v143
	v_exp_f32_e32 v152, v82
	v_sub_f32_e32 v82, v161, v143
	v_exp_f32_e32 v156, v82
	v_sub_f32_e32 v82, v162, v143
	v_exp_f32_e32 v160, v82
	v_sub_f32_e32 v82, v163, v143
	v_exp_f32_e32 v162, v82
	v_sub_f32_e32 v82, v166, v143
	v_exp_f32_e32 v164, v82
	v_sub_f32_e32 v82, v167, v143
	v_exp_f32_e32 v166, v82
	v_sub_f32_e32 v82, v168, v143
	v_exp_f32_e32 v168, v82
	v_sub_f32_e32 v82, v169, v143
	v_exp_f32_e32 v170, v82
	v_sub_f32_e32 v82, v174, v143
	v_exp_f32_e32 v172, v82
	v_sub_f32_e32 v82, v175, v143
	v_exp_f32_e32 v174, v82
	v_sub_f32_e32 v82, v176, v143
	v_exp_f32_e32 v176, v82
	v_sub_f32_e32 v82, v177, v143
	v_exp_f32_e32 v178, v82
	v_sub_f32_e32 v82, v180, v143
	v_exp_f32_e32 v180, v82
	v_sub_f32_e32 v82, v181, v143
	v_exp_f32_e32 v192, v82
	v_sub_f32_e32 v82, v182, v143
	v_exp_f32_e32 v194, v82
	v_sub_f32_e32 v82, v183, v143
	v_exp_f32_e32 v196, v82
	v_mul_f32_e32 v84, v68, v158
	v_mul_f32_e32 v85, v69, v158
	v_mul_f32_e32 v82, v66, v158
	v_mul_f32_e32 v83, v67, v158
	v_mul_f32_e32 v88, v72, v158
	v_mul_f32_e32 v89, v73, v158
	v_mul_f32_e32 v86, v70, v158
	v_mul_f32_e32 v87, v71, v158
	v_mul_f32_e32 v76, v76, v158
	v_mul_f32_e32 v77, v77, v158
	v_mul_f32_e32 v74, v74, v158
	v_mul_f32_e32 v75, v75, v158
	v_mul_f32_e32 v68, v80, v158
	v_mul_f32_e32 v69, v81, v158
	v_mul_f32_e32 v66, v78, v158
	v_mul_f32_e32 v67, v79, v158
	v_max_f32_e32 v159, v92, v92
	v_max_f32_e32 v157, v159, v157
	v_max_f32_e32 v159, v97, v97
	v_max_f32_e32 v161, v96, v96
	v_max_f32_e32 v159, v161, v159
	v_max3_f32 v159, v94, v95, v159
	v_max3_f32 v153, v153, v157, v159
	v_max_f32_e32 v157, v101, v101
	v_max_f32_e32 v159, v100, v100
	v_max_f32_e32 v157, v159, v157
	v_max_f32_e32 v159, v105, v105
	v_max_f32_e32 v161, v104, v104
	v_max_f32_e32 v159, v161, v159
	v_max3_f32 v157, v98, v99, v157
	v_max3_f32 v159, v102, v103, v159
	v_max3_f32 v153, v153, v157, v159
	v_cvt_pk_bf16_f32 v70, v152, v156
	v_cvt_pk_bf16_f32 v71, v160, v162
	v_cvt_pk_bf16_f32 v72, v164, v166
	v_cvt_pk_bf16_f32 v73, v168, v170
	s_waitcnt lgkmcnt(0)
	v_max_f32_e32 v157, v157, v157
	v_mov_b32_e32 v157, v153
	s_nop 1
	v_permlane16_swap_b32_e32 v153, v157
	v_max_f32_e32 v153, v153, v157
	v_mov_b32_e32 v157, v153
	s_nop 1
	v_permlane32_swap_b32_e32 v153, v157
	v_max3_f32 v182, v127, v153, v157
	v_sub_f32_e32 v90, v90, v182
	v_exp_f32_e32 v153, v90
	v_sub_f32_e32 v90, v91, v182
	v_exp_f32_e32 v157, v90
	v_sub_f32_e32 v90, v92, v182
	v_exp_f32_e32 v161, v90
	v_sub_f32_e32 v90, v93, v182
	v_exp_f32_e32 v163, v90
	v_sub_f32_e32 v90, v94, v182
	v_exp_f32_e32 v165, v90
	v_sub_f32_e32 v90, v95, v182
	v_exp_f32_e32 v167, v90
	v_add_f32_e32 v90, 0, v152
	v_add_f32_e32 v91, 0, v153
	v_sub_f32_e32 v92, v96, v182
	v_add_f32_e32 v90, v156, v90
	v_add_f32_e32 v91, v157, v91
	v_exp_f32_e32 v169, v92
	v_add_f32_e32 v90, v160, v90
	v_add_f32_e32 v91, v161, v91
	v_sub_f32_e32 v92, v97, v182
	v_add_f32_e32 v90, v162, v90
	v_add_f32_e32 v91, v163, v91
	v_exp_f32_e32 v171, v92
	v_sub_f32_e32 v92, v98, v182
	v_add_f32_e32 v90, v164, v90
	v_add_f32_e32 v91, v165, v91
	v_exp_f32_e32 v173, v92
	v_sub_f32_e32 v92, v99, v182
	v_add_f32_e32 v90, v166, v90
	v_add_f32_e32 v91, v167, v91
	v_exp_f32_e32 v175, v92
	v_sub_f32_e32 v92, v100, v182
	v_exp_f32_e32 v177, v92
	v_sub_f32_e32 v92, v101, v182
	v_add_f32_e32 v90, v168, v90
	v_add_f32_e32 v91, v169, v91
	v_exp_f32_e32 v179, v92
	v_sub_f32_e32 v92, v102, v182
	v_add_f32_e32 v90, v170, v90
	v_add_f32_e32 v91, v171, v91
	v_exp_f32_e32 v181, v92
	v_sub_f32_e32 v92, v103, v182
	v_add_f32_e32 v90, v172, v90
	v_add_f32_e32 v91, v173, v91
	v_exp_f32_e32 v193, v92
	v_sub_f32_e32 v92, v104, v182
	v_add_f32_e32 v90, v174, v90
	v_add_f32_e32 v91, v175, v91
	v_sub_f32_e32 v127, v127, v182
	v_exp_f32_e32 v195, v92
	v_sub_f32_e32 v92, v105, v182
	v_add_f32_e32 v90, v176, v90
	v_add_f32_e32 v91, v177, v91
	v_exp_f32_e32 v159, v127
	v_exp_f32_e32 v197, v92
	v_add_f32_e32 v90, v178, v90
	v_add_f32_e32 v91, v179, v91
	v_cvt_pk_bf16_f32 v78, v172, v174
	v_add_f32_e32 v90, v180, v90
	v_add_f32_e32 v91, v181, v91
	v_mov_b32_e32 v98, v159
	v_add_f32_e32 v90, v192, v90
	v_add_f32_e32 v91, v193, v91
	v_mul_f32_e32 v92, v52, v98
	v_mul_f32_e32 v93, v53, v98
	v_add_f32_e32 v90, v194, v90
	v_add_f32_e32 v91, v195, v91
	v_mul_f32_e32 v96, v56, v98
	v_mul_f32_e32 v97, v57, v98
	v_add_f32_e32 v90, v196, v90
	v_add_f32_e32 v91, v197, v91
	v_mul_f32_e32 v94, v54, v98
	v_mul_f32_e32 v95, v55, v98
	v_pk_fma_f32 v[150:151], v[150:151], v[158:159], v[90:91]
	v_mul_f32_e32 v90, v50, v98
	v_mul_f32_e32 v91, v51, v98
	v_mul_f32_e32 v60, v60, v98
	v_mul_f32_e32 v61, v61, v98
	v_mul_f32_e32 v58, v58, v98
	v_mul_f32_e32 v59, v59, v98
	v_mul_f32_e32 v52, v64, v98
	v_mul_f32_e32 v53, v65, v98
	v_mul_f32_e32 v50, v62, v98
	v_mul_f32_e32 v51, v63, v98
	v_lshlrev_b32_e32 v98, 1, v187
	v_add3_u32 v127, s18, v98, v189
	ds_read_b64_tr_b16 v[100:101], v127 offset:15872
	ds_read_b64_tr_b16 v[98:99], v127 offset:13312
	ds_read_b64_tr_b16 v[102:103], v127 offset:13320
	v_cvt_pk_bf16_f32 v54, v153, v157
	v_cvt_pk_bf16_f32 v55, v161, v163
	v_cvt_pk_bf16_f32 v56, v165, v167
	v_cvt_pk_bf16_f32 v57, v169, v171
	s_waitcnt lgkmcnt(1)
	v_mfma_f32_16x16x32_bf16 v[82:85], v[98:101], v[70:73], v[82:85]
	ds_read_b64_tr_b16 v[104:105], v127 offset:15880
	v_cvt_pk_bf16_f32 v79, v176, v178
	v_cvt_pk_bf16_f32 v80, v180, v192
	v_mfma_f32_16x16x32_bf16 v[90:93], v[98:101], v[54:57], v[90:93]
	ds_read_b64_tr_b16 v[98:99], v127 offset:13376
	ds_read_b64_tr_b16 v[100:101], v127 offset:15936
	v_cvt_pk_bf16_f32 v81, v194, v196
	v_cvt_pk_bf16_f32 v62, v173, v175
	s_waitcnt lgkmcnt(0)
	v_mfma_f32_16x16x32_bf16 v[74:77], v[98:101], v[70:73], v[74:77]
	v_cvt_pk_bf16_f32 v63, v177, v179
	v_cvt_pk_bf16_f32 v64, v181, v193
	v_cvt_pk_bf16_f32 v65, v195, v197
	v_mfma_f32_16x16x32_bf16 v[58:61], v[98:101], v[54:57], v[58:61]
	ds_read_b64_tr_b16 v[98:99], v127 offset:13384
	ds_read_b64_tr_b16 v[100:101], v127 offset:15944
	v_mfma_f32_16x16x32_bf16 v[86:89], v[102:105], v[70:73], v[86:89]
	v_mfma_f32_16x16x32_bf16 v[94:97], v[102:105], v[54:57], v[94:97]
	s_waitcnt lgkmcnt(0)
	v_mfma_f32_16x16x32_bf16 v[102:105], v[98:101], v[70:73], v[66:69]
	v_mfma_f32_16x16x32_bf16 v[98:101], v[98:101], v[54:57], v[50:53]
	s_nop 2
	ds_read_b64_tr_b16 v[50:51], v127 offset:18432
	ds_read_b64_tr_b16 v[52:53], v127 offset:20992
	ds_read_b64_tr_b16 v[54:55], v127 offset:18440
	ds_read_b64_tr_b16 v[56:57], v127 offset:21000
	s_waitcnt lgkmcnt(2)
	v_mfma_f32_16x16x32_bf16 v[66:69], v[50:53], v[78:81], v[82:85]
	s_nop 2
	ds_read_b64_tr_b16 v[82:83], v127 offset:18496
	ds_read_b64_tr_b16 v[84:85], v127 offset:21056
	s_waitcnt lgkmcnt(0)
	v_mfma_f32_16x16x32_bf16 v[74:77], v[82:85], v[78:81], v[74:77]
	v_mfma_f32_16x16x32_bf16 v[58:61], v[82:85], v[62:65], v[58:61]
	ds_read_b64_tr_b16 v[82:83], v127 offset:18504
	ds_read_b64_tr_b16 v[84:85], v127 offset:21064
	v_mov_b32_e32 v127, v182
	v_mfma_f32_16x16x32_bf16 v[50:53], v[50:53], v[62:65], v[90:93]
	v_mfma_f32_16x16x32_bf16 v[70:73], v[54:57], v[78:81], v[86:89]
	v_mfma_f32_16x16x32_bf16 v[54:57], v[54:57], v[62:65], v[94:97]
	s_waitcnt lgkmcnt(0)
	v_mfma_f32_16x16x32_bf16 v[78:81], v[82:85], v[78:81], v[102:105]
	v_mfma_f32_16x16x32_bf16 v[62:65], v[82:85], v[62:65], v[98:101]
	v_mov_b32_e32 v82, v143
	s_branch .LBB0_1042

.LBB0_1058:
	s_waitcnt vmcnt(8)
	ds_bpermute_b32 v0, v190, v150
	s_mov_b32 s47, s25
	v_lshl_add_u64 v[138:139], v[120:121], 0, s[46:47]
	s_waitcnt vmcnt(7)
	v_lshlrev_b64 v[6:7], 11, v[148:149]
	s_waitcnt vmcnt(6)
	v_lshl_add_u64 v[8:9], v[138:139], 0, v[6:7]
	s_waitcnt lgkmcnt(0)
	v_add_f32_e32 v0, v150, v0
	v_mov_b32_e32 v1, v0
	s_nop 1
	v_permlane32_swap_b32_e32 v0, v1
	v_add_f32_e32 v0, v0, v1
	v_div_scale_f32 v1, s[6:7], v0, v0, 1.0
	v_rcp_f32_e32 v2, v1
	v_div_scale_f32 v3, vcc, 1.0, v0, 1.0
	v_or_b32_e32 v6, 0x8000, v6
	v_fma_f32 v4, -v1, v2, 1.0
	v_fmac_f32_e32 v2, v4, v2
	v_mul_f32_e32 v4, v3, v2
	v_fma_f32 v5, -v1, v4, v3
	v_fmac_f32_e32 v4, v5, v2
	v_fma_f32 v1, -v1, v4, v3
	v_div_fmas_f32 v1, v1, v2, v4
	v_div_fixup_f32 v4, v1, v0, 1.0
	v_mul_f32_e32 v2, v68, v4
	v_mul_f32_e32 v3, v69, v4
	v_mul_f32_e32 v0, v66, v4
	v_mul_f32_e32 v1, v67, v4
	v_mul_f32_e32 v10, v72, v4
	v_mul_f32_e32 v11, v73, v4
	v_cvt_pk_bf16_f32 v0, v0, v1
	v_cvt_pk_bf16_f32 v1, v2, v3
	v_mul_f32_e32 v2, v70, v4
	v_mul_f32_e32 v3, v71, v4
	v_lshl_add_u64 v[6:7], v[138:139], 0, v[6:7]
	v_cvt_pk_bf16_f32 v2, v2, v3
	v_cvt_pk_bf16_f32 v3, v10, v11
	global_store_dwordx4 v[8:9], v[0:3], off
	s_nop 1
	v_mul_f32_e32 v2, v76, v4
	v_mul_f32_e32 v3, v77, v4
	v_mul_f32_e32 v0, v74, v4
	v_mul_f32_e32 v1, v75, v4
	ds_bpermute_b32 v5, v190, v151
	v_cvt_pk_bf16_f32 v0, v0, v1
	v_cvt_pk_bf16_f32 v1, v2, v3
	s_waitcnt vmcnt(0)
	v_mov_b32_e32 v32, 0
	v_mov_b32_e32 v24, 0
	s_waitcnt lgkmcnt(0)
	v_mul_f32_e32 v2, v78, v4
	v_mul_f32_e32 v3, v79, v4
	v_mul_f32_e32 v10, v80, v4
	v_mul_f32_e32 v11, v81, v4
	v_cvt_pk_bf16_f32 v2, v2, v3
	v_add_f32_e32 v3, v151, v5
	v_mov_b32_e32 v4, v3
	s_nop 1
	v_permlane32_swap_b32_e32 v3, v4
	v_add_f32_e32 v12, v3, v4
	v_div_scale_f32 v13, s[6:7], v12, v12, 1.0
	v_rcp_f32_e32 v14, v13
	v_cvt_pk_bf16_f32 v3, v10, v11
	v_lshl_add_u64 v[4:5], v[8:9], 0, 64
	global_store_dwordx4 v[4:5], v[0:3], off
	s_nop 1
	v_fma_f32 v0, -v13, v14, 1.0
	v_fmac_f32_e32 v14, v0, v14
	v_div_scale_f32 v0, vcc, 1.0, v12, 1.0
	v_mul_f32_e32 v1, v0, v14
	v_fma_f32 v2, -v13, v1, v0
	v_fmac_f32_e32 v1, v2, v14
	v_fma_f32 v0, -v13, v1, v0
	v_div_fmas_f32 v0, v0, v14, v1
	v_div_fixup_f32 v4, v0, v12, 1.0
	v_mul_f32_e32 v2, v52, v4
	v_mul_f32_e32 v3, v53, v4
	v_mul_f32_e32 v0, v50, v4
	v_mul_f32_e32 v1, v51, v4
	s_sub_i32 s6, 7, s59
	v_cvt_pk_bf16_f32 v0, v0, v1
	v_cvt_pk_bf16_f32 v1, v2, v3
	v_mul_f32_e32 v8, v56, v4
	v_mul_f32_e32 v9, v57, v4
	v_mul_f32_e32 v2, v54, v4
	v_mul_f32_e32 v3, v55, v4
	s_lshl_b32 s7, s6, 8
	v_cvt_pk_bf16_f32 v2, v2, v3
	v_cvt_pk_bf16_f32 v3, v8, v9
	s_add_i32 s20, s7, s56
	global_store_dwordx4 v[6:7], v[0:3], off
	s_nop 1
	v_mul_f32_e32 v2, v60, v4
	v_mul_f32_e32 v3, v61, v4
	v_mul_f32_e32 v0, v58, v4
	v_mul_f32_e32 v1, v59, v4
	s_ashr_i32 s21, s20, 31
	v_cvt_pk_bf16_f32 v0, v0, v1
	v_cvt_pk_bf16_f32 v1, v2, v3
	v_mul_f32_e32 v8, v64, v4
	v_mul_f32_e32 v9, v65, v4
	v_mul_f32_e32 v2, v62, v4
	v_mul_f32_e32 v3, v63, v4
	v_lshl_add_u64 v[148:149], v[106:107], 0, s[20:21]
	s_movk_i32 s7, 0x600
	v_cvt_pk_bf16_f32 v2, v2, v3
	v_cvt_pk_bf16_f32 v3, v8, v9
	v_mad_u64_u32 v[8:9], s[20:21], v148, s7, v[140:141]
	v_mad_i32_i24 v9, v149, s7, v9
	s_mov_b64 s[20:21], 0x6000
	v_add_co_u32_e32 v12, vcc, 0x6000, v8
	v_lshl_add_u64 v[4:5], v[6:7], 0, 64
	v_lshl_add_u64 v[20:21], v[8:9], 0, s[20:21]
	v_addc_co_u32_e32 v13, vcc, 0, v9, vcc
	global_store_dwordx4 v[4:5], v[0:3], off
	s_nop 1
	s_barrier
	global_load_dwordx4 v[0:3], v[8:9], off offset:64
	global_load_dwordx4 v[4:7], v[8:9], off offset:128
	s_nop 0
	global_load_dwordx4 v[8:11], v[8:9], off
	s_nop 0
	global_load_dwordx4 v[12:15], v[12:13], off
	s_nop 0
	global_load_dwordx4 v[16:19], v[20:21], off offset:64
	s_nop 0
	global_load_dwordx4 v[20:23], v[20:21], off offset:128
	s_nop 0
	global_load_dwordx4 v[28:31], v[132:133], off
	v_mov_b32_e32 v25, 0
	v_mov_b32_e32 v26, 0
	v_mov_b32_e32 v27, 0
	s_and_saveexec_b64 s[46:47], s[40:41]
	s_cbranch_execz .LBB0_1060
	global_load_dwordx4 v[24:27], v[134:135], off

.LBB0_1077:
	v_add3_u32 v83, s18, v186, v188
	ds_read_b128 v[84:87], v83
	ds_read_b128 v[92:95], v83 offset:64
	s_waitcnt lgkmcnt(1)
	v_mfma_f32_16x16x32_bf16 v[88:91], v[84:87], v[8:11], 0
	ds_read_b128 v[98:101], v83 offset:3392
	ds_read_b128 v[102:105], v83 offset:6720
	ds_read_b128 v[144:147], v83 offset:10048
	v_mfma_f32_16x16x32_bf16 v[84:87], v[84:87], v[12:15], 0
	s_waitcnt lgkmcnt(3)
	v_mfma_f32_16x16x32_bf16 v[88:91], v[92:95], v[0:3], v[88:91]
	v_mfma_f32_16x16x32_bf16 v[84:87], v[92:95], v[16:19], v[84:87]
	ds_read_b128 v[92:95], v83 offset:128
	s_waitcnt lgkmcnt(0)
	v_mfma_f32_16x16x32_bf16 v[150:153], v[92:95], v[4:7], v[88:91]
	v_mfma_f32_16x16x32_bf16 v[90:93], v[92:95], v[20:23], v[84:87]
	s_nop 3
	ds_read_b128 v[84:87], v83 offset:3328
	s_waitcnt lgkmcnt(0)
	v_mfma_f32_16x16x32_bf16 v[94:97], v[84:87], v[8:11], 0
	v_mfma_f32_16x16x32_bf16 v[84:87], v[84:87], v[12:15], 0
	v_mfma_f32_16x16x32_bf16 v[94:97], v[98:101], v[0:3], v[94:97]
	v_mfma_f32_16x16x32_bf16 v[84:87], v[98:101], v[16:19], v[84:87]
	ds_read_b128 v[98:101], v83 offset:3456
	s_waitcnt lgkmcnt(0)
	v_mfma_f32_16x16x32_bf16 v[158:161], v[98:101], v[4:7], v[94:97]
	v_mfma_f32_16x16x32_bf16 v[94:97], v[98:101], v[20:23], v[84:87]
	s_nop 3
	ds_read_b128 v[84:87], v83 offset:6656
	s_waitcnt lgkmcnt(0)
	v_mfma_f32_16x16x32_bf16 v[98:101], v[84:87], v[8:11], 0
	v_mfma_f32_16x16x32_bf16 v[84:87], v[84:87], v[12:15], 0
	v_mfma_f32_16x16x32_bf16 v[98:101], v[102:105], v[0:3], v[98:101]
	v_mfma_f32_16x16x32_bf16 v[84:87], v[102:105], v[16:19], v[84:87]
	ds_read_b128 v[102:105], v83 offset:6784
	s_waitcnt lgkmcnt(0)
	v_mfma_f32_16x16x32_bf16 v[166:169], v[102:105], v[4:7], v[98:101]
	v_mfma_f32_16x16x32_bf16 v[98:101], v[102:105], v[20:23], v[84:87]
	s_nop 3
	ds_read_b128 v[84:87], v83 offset:9984
	s_waitcnt lgkmcnt(0)
	v_mfma_f32_16x16x32_bf16 v[102:105], v[84:87], v[8:11], 0
	v_mfma_f32_16x16x32_bf16 v[84:87], v[84:87], v[12:15], 0
	v_mfma_f32_16x16x32_bf16 v[102:105], v[144:147], v[0:3], v[102:105]
	v_mfma_f32_16x16x32_bf16 v[84:87], v[144:147], v[16:19], v[84:87]
	ds_read_b128 v[144:147], v83 offset:10112
	v_max_f32_e32 v83, v151, v151
	s_waitcnt lgkmcnt(0)
	v_mfma_f32_16x16x32_bf16 v[178:181], v[144:147], v[4:7], v[102:105]
	v_mfma_f32_16x16x32_bf16 v[102:105], v[144:147], v[20:23], v[84:87]
	v_max_f32_e32 v145, v91, v91
	s_nop 1
	v_max_f32_e32 v84, v150, v150
	v_max_f32_e32 v83, v84, v83
	v_max_f32_e32 v84, v153, v153
	v_max_f32_e32 v85, v152, v152
	v_max_f32_e32 v84, v85, v84
	v_max_f32_e32 v85, v161, v161
	v_max_f32_e32 v86, v160, v160
	v_max_f32_e32 v85, v86, v85
	v_max3_f32 v85, v158, v159, v85
	v_max3_f32 v83, v83, v84, v85
	v_max_f32_e32 v84, v169, v169
	v_max_f32_e32 v85, v168, v168
	v_max_f32_e32 v84, v85, v84
	v_max_f32_e32 v85, v181, v181
	v_max_f32_e32 v86, v180, v180
	v_max_f32_e32 v85, v86, v85
	v_max3_f32 v84, v166, v167, v84
	v_max3_f32 v85, v178, v179, v85
	v_max3_f32 v83, v83, v84, v85
	s_waitcnt lgkmcnt(0)
	v_max_f32_e32 v84, v84, v84
	v_mov_b32_e32 v84, v83
	s_nop 1
	v_permlane16_swap_b32_e32 v83, v84
	v_max_f32_e32 v83, v83, v84
	v_mov_b32_e32 v84, v83
	s_nop 1
	v_permlane32_swap_b32_e32 v83, v84
	v_max3_f32 v176, v82, v83, v84
	v_sub_f32_e32 v82, v82, v176
	v_exp_f32_e32 v146, v82
	v_sub_f32_e32 v82, v150, v176
	v_exp_f32_e32 v142, v82
	v_sub_f32_e32 v82, v151, v176
	v_exp_f32_e32 v144, v82
	v_sub_f32_e32 v82, v152, v176
	v_exp_f32_e32 v150, v82
	v_sub_f32_e32 v82, v153, v176
	v_exp_f32_e32 v152, v82
	v_sub_f32_e32 v82, v158, v176
	v_exp_f32_e32 v156, v82
	v_sub_f32_e32 v82, v159, v176
	v_exp_f32_e32 v158, v82
	v_sub_f32_e32 v82, v160, v176
	v_exp_f32_e32 v160, v82
	v_sub_f32_e32 v82, v161, v176
	v_exp_f32_e32 v162, v82
	v_sub_f32_e32 v82, v166, v176
	v_exp_f32_e32 v164, v82
	v_sub_f32_e32 v82, v167, v176
	v_exp_f32_e32 v166, v82
	v_sub_f32_e32 v82, v168, v176
	v_exp_f32_e32 v168, v82
	v_sub_f32_e32 v82, v169, v176
	v_exp_f32_e32 v170, v82
	v_sub_f32_e32 v82, v178, v176
	v_exp_f32_e32 v172, v82
	v_sub_f32_e32 v82, v179, v176
	v_exp_f32_e32 v174, v82
	v_sub_f32_e32 v82, v180, v176
	v_exp_f32_e32 v178, v82
	v_sub_f32_e32 v82, v181, v176
	v_exp_f32_e32 v180, v82
	v_mul_f32_e32 v84, v68, v146
	v_mul_f32_e32 v85, v69, v146
	v_mul_f32_e32 v82, v66, v146
	v_mul_f32_e32 v83, v67, v146
	v_mul_f32_e32 v88, v72, v146
	v_mul_f32_e32 v89, v73, v146
	v_mul_f32_e32 v86, v70, v146
	v_mul_f32_e32 v87, v71, v146
	v_mul_f32_e32 v76, v76, v146
	v_mul_f32_e32 v77, v77, v146
	v_mul_f32_e32 v74, v74, v146
	v_mul_f32_e32 v75, v75, v146
	v_mul_f32_e32 v68, v80, v146
	v_mul_f32_e32 v69, v81, v146
	v_mul_f32_e32 v66, v78, v146
	v_mul_f32_e32 v67, v79, v146
	v_max_f32_e32 v147, v90, v90
	v_max_f32_e32 v145, v147, v145
	v_max_f32_e32 v147, v93, v93
	v_max_f32_e32 v151, v92, v92
	v_max_f32_e32 v147, v151, v147
	v_max_f32_e32 v151, v97, v97
	v_max_f32_e32 v153, v96, v96
	v_max_f32_e32 v151, v153, v151
	v_max3_f32 v151, v94, v95, v151
	v_max3_f32 v145, v145, v147, v151
	v_max_f32_e32 v147, v101, v101
	v_max_f32_e32 v151, v100, v100
	v_max_f32_e32 v147, v151, v147
	v_max_f32_e32 v151, v105, v105
	v_max_f32_e32 v153, v104, v104
	v_max_f32_e32 v151, v153, v151
	v_max3_f32 v147, v98, v99, v147
	v_max3_f32 v151, v102, v103, v151
	v_max3_f32 v145, v145, v147, v151
	v_cvt_pk_bf16_f32 v70, v142, v144
	v_cvt_pk_bf16_f32 v71, v150, v152
	v_cvt_pk_bf16_f32 v72, v156, v158
	v_cvt_pk_bf16_f32 v73, v160, v162
	s_waitcnt lgkmcnt(0)
	v_max_f32_e32 v147, v147, v147
	v_mov_b32_e32 v147, v145
	s_nop 1
	v_permlane16_swap_b32_e32 v145, v147
	v_max_f32_e32 v145, v145, v147
	v_mov_b32_e32 v147, v145
	s_nop 1
	v_permlane32_swap_b32_e32 v145, v147
	v_max3_f32 v177, v143, v145, v147
	v_sub_f32_e32 v143, v143, v177
	v_sub_f32_e32 v90, v90, v177
	v_exp_f32_e32 v147, v143
	v_exp_f32_e32 v143, v90
	v_sub_f32_e32 v90, v91, v177
	v_exp_f32_e32 v145, v90
	v_sub_f32_e32 v90, v92, v177
	v_exp_f32_e32 v151, v90
	v_sub_f32_e32 v90, v93, v177
	v_exp_f32_e32 v153, v90
	v_sub_f32_e32 v90, v94, v177
	v_exp_f32_e32 v157, v90
	v_sub_f32_e32 v90, v95, v177
	v_exp_f32_e32 v159, v90
	v_add_f32_e32 v90, 0, v142
	v_add_f32_e32 v91, 0, v143
	v_sub_f32_e32 v92, v96, v177
	v_add_f32_e32 v90, v144, v90
	v_add_f32_e32 v91, v145, v91
	v_exp_f32_e32 v161, v92
	v_add_f32_e32 v90, v150, v90
	v_add_f32_e32 v91, v151, v91
	v_sub_f32_e32 v92, v97, v177
	v_add_f32_e32 v90, v152, v90
	v_add_f32_e32 v91, v153, v91
	v_exp_f32_e32 v163, v92
	v_sub_f32_e32 v92, v98, v177
	v_add_f32_e32 v90, v156, v90
	v_add_f32_e32 v91, v157, v91
	v_exp_f32_e32 v165, v92
	v_sub_f32_e32 v92, v99, v177
	v_add_f32_e32 v90, v158, v90
	v_add_f32_e32 v91, v159, v91
	v_exp_f32_e32 v167, v92
	v_sub_f32_e32 v92, v100, v177
	v_exp_f32_e32 v169, v92
	v_sub_f32_e32 v92, v101, v177
	v_add_f32_e32 v90, v160, v90
	v_add_f32_e32 v91, v161, v91
	v_exp_f32_e32 v171, v92
	v_sub_f32_e32 v92, v102, v177
	v_add_f32_e32 v90, v162, v90
	v_add_f32_e32 v91, v163, v91
	v_exp_f32_e32 v173, v92
	v_sub_f32_e32 v92, v103, v177
	v_add_f32_e32 v90, v164, v90
	v_add_f32_e32 v91, v165, v91
	v_exp_f32_e32 v175, v92
	v_sub_f32_e32 v92, v104, v177
	v_add_f32_e32 v90, v166, v90
	v_add_f32_e32 v91, v167, v91
	v_exp_f32_e32 v179, v92
	v_sub_f32_e32 v92, v105, v177
	v_add_f32_e32 v90, v168, v90
	v_add_f32_e32 v91, v169, v91
	v_exp_f32_e32 v181, v92
	v_add_f32_e32 v90, v170, v90
	v_add_f32_e32 v91, v171, v91
	v_mov_b32_e32 v98, v147
	v_add_f32_e32 v90, v172, v90
	v_add_f32_e32 v91, v173, v91
	v_add3_u32 v142, s18, v127, v189
	v_add_f32_e32 v90, v174, v90
	v_add_f32_e32 v91, v175, v91
	v_mul_f32_e32 v92, v52, v98
	v_mul_f32_e32 v93, v53, v98
	v_add_f32_e32 v90, v178, v90
	v_add_f32_e32 v91, v179, v91
	v_mul_f32_e32 v96, v56, v98
	v_mul_f32_e32 v97, v57, v98
	v_add_f32_e32 v90, v180, v90
	v_add_f32_e32 v91, v181, v91
	v_mul_f32_e32 v94, v54, v98
	v_mul_f32_e32 v95, v55, v98
	v_pk_fma_f32 v[140:141], v[140:141], v[146:147], v[90:91]
	v_mul_f32_e32 v90, v50, v98
	v_mul_f32_e32 v91, v51, v98
	v_mul_f32_e32 v60, v60, v98
	v_mul_f32_e32 v61, v61, v98
	v_mul_f32_e32 v58, v58, v98
	v_mul_f32_e32 v59, v59, v98
	v_mul_f32_e32 v52, v64, v98
	v_mul_f32_e32 v53, v65, v98
	v_mul_f32_e32 v50, v62, v98
	v_mul_f32_e32 v51, v63, v98
	ds_read_b64_tr_b16 v[100:101], v142 offset:15872
	ds_read_b64_tr_b16 v[98:99], v142 offset:13312
	ds_read_b64_tr_b16 v[102:103], v142 offset:13320
	v_cvt_pk_bf16_f32 v54, v143, v145
	v_cvt_pk_bf16_f32 v55, v151, v153
	v_cvt_pk_bf16_f32 v56, v157, v159
	v_cvt_pk_bf16_f32 v57, v161, v163
	s_waitcnt lgkmcnt(1)
	v_mfma_f32_16x16x32_bf16 v[82:85], v[98:101], v[70:73], v[82:85]
	ds_read_b64_tr_b16 v[104:105], v142 offset:15880
	v_cvt_pk_bf16_f32 v78, v164, v166
	v_cvt_pk_bf16_f32 v79, v168, v170
	v_mfma_f32_16x16x32_bf16 v[90:93], v[98:101], v[54:57], v[90:93]
	ds_read_b64_tr_b16 v[98:99], v142 offset:13376
	ds_read_b64_tr_b16 v[100:101], v142 offset:15936
	v_cvt_pk_bf16_f32 v80, v172, v174
	v_cvt_pk_bf16_f32 v81, v178, v180
	s_waitcnt lgkmcnt(0)
	v_mfma_f32_16x16x32_bf16 v[74:77], v[98:101], v[70:73], v[74:77]
	v_cvt_pk_bf16_f32 v62, v165, v167
	v_cvt_pk_bf16_f32 v63, v169, v171
	v_cvt_pk_bf16_f32 v64, v173, v175
	v_mfma_f32_16x16x32_bf16 v[58:61], v[98:101], v[54:57], v[58:61]
	ds_read_b64_tr_b16 v[98:99], v142 offset:13384
	ds_read_b64_tr_b16 v[100:101], v142 offset:15944
	v_cvt_pk_bf16_f32 v65, v179, v181
	v_mov_b32_e32 v143, v177
	v_mfma_f32_16x16x32_bf16 v[86:89], v[102:105], v[70:73], v[86:89]
	v_mfma_f32_16x16x32_bf16 v[94:97], v[102:105], v[54:57], v[94:97]
	s_waitcnt lgkmcnt(0)
	v_mfma_f32_16x16x32_bf16 v[102:105], v[98:101], v[70:73], v[66:69]
	v_mfma_f32_16x16x32_bf16 v[98:101], v[98:101], v[54:57], v[50:53]
	s_nop 2
	ds_read_b64_tr_b16 v[50:51], v142 offset:18432
	ds_read_b64_tr_b16 v[52:53], v142 offset:20992
	ds_read_b64_tr_b16 v[54:55], v142 offset:18440
	ds_read_b64_tr_b16 v[56:57], v142 offset:21000
	s_waitcnt lgkmcnt(2)
	v_mfma_f32_16x16x32_bf16 v[66:69], v[50:53], v[78:81], v[82:85]
	s_nop 2
	ds_read_b64_tr_b16 v[82:83], v142 offset:18496
	ds_read_b64_tr_b16 v[84:85], v142 offset:21056
	s_waitcnt lgkmcnt(0)
	v_mfma_f32_16x16x32_bf16 v[74:77], v[82:85], v[78:81], v[74:77]
	v_mfma_f32_16x16x32_bf16 v[58:61], v[82:85], v[62:65], v[58:61]
	ds_read_b64_tr_b16 v[82:83], v142 offset:18504
	ds_read_b64_tr_b16 v[84:85], v142 offset:21064
	v_mfma_f32_16x16x32_bf16 v[50:53], v[50:53], v[62:65], v[90:93]
	v_mfma_f32_16x16x32_bf16 v[70:73], v[54:57], v[78:81], v[86:89]
	v_mfma_f32_16x16x32_bf16 v[54:57], v[54:57], v[62:65], v[94:97]
	s_waitcnt lgkmcnt(0)
	v_mfma_f32_16x16x32_bf16 v[78:81], v[82:85], v[78:81], v[102:105]
	v_mfma_f32_16x16x32_bf16 v[62:65], v[82:85], v[62:65], v[98:101]
	v_mov_b32_e32 v82, v176
	s_add_i32 s6, s46, -2
	s_cmp_ge_i32 s6, s52
	s_cbranch_scc1 .LBB0_1064
.LBB0_1078:
	s_and_b32 s6, s6, 3
	s_mulk_i32 s6, 0x5c00
	s_add_i32 s18, s6, 0
	v_add3_u32 v83, s18, v186, v188
	ds_read_b128 v[84:87], v83
	ds_read_b128 v[92:95], v83 offset:64
	v_add3_u32 v127, s18, v127, v189
	s_waitcnt lgkmcnt(1)
	v_mfma_f32_16x16x32_bf16 v[88:91], v[84:87], v[8:11], 0
	ds_read_b128 v[98:101], v83 offset:3392
	ds_read_b128 v[102:105], v83 offset:6720
	ds_read_b128 v[144:147], v83 offset:10048
	v_mfma_f32_16x16x32_bf16 v[84:87], v[84:87], v[12:15], 0
	s_waitcnt lgkmcnt(3)
	v_mfma_f32_16x16x32_bf16 v[88:91], v[92:95], v[0:3], v[88:91]
	v_mfma_f32_16x16x32_bf16 v[84:87], v[92:95], v[16:19], v[84:87]
	ds_read_b128 v[92:95], v83 offset:128
	s_waitcnt lgkmcnt(0)
	v_mfma_f32_16x16x32_bf16 v[150:153], v[92:95], v[4:7], v[88:91]
	v_mfma_f32_16x16x32_bf16 v[90:93], v[92:95], v[20:23], v[84:87]
	s_nop 3
	ds_read_b128 v[84:87], v83 offset:3328
	s_waitcnt lgkmcnt(0)
	v_mfma_f32_16x16x32_bf16 v[94:97], v[84:87], v[8:11], 0
	v_mfma_f32_16x16x32_bf16 v[84:87], v[84:87], v[12:15], 0
	v_mfma_f32_16x16x32_bf16 v[94:97], v[98:101], v[0:3], v[94:97]
	v_mfma_f32_16x16x32_bf16 v[84:87], v[98:101], v[16:19], v[84:87]
	ds_read_b128 v[98:101], v83 offset:3456
	s_waitcnt lgkmcnt(0)
	v_mfma_f32_16x16x32_bf16 v[158:161], v[98:101], v[4:7], v[94:97]
	v_mfma_f32_16x16x32_bf16 v[94:97], v[98:101], v[20:23], v[84:87]
	s_nop 3
	ds_read_b128 v[84:87], v83 offset:6656
	s_waitcnt lgkmcnt(0)
	v_mfma_f32_16x16x32_bf16 v[98:101], v[84:87], v[8:11], 0
	v_mfma_f32_16x16x32_bf16 v[84:87], v[84:87], v[12:15], 0
	v_mfma_f32_16x16x32_bf16 v[98:101], v[102:105], v[0:3], v[98:101]
	v_mfma_f32_16x16x32_bf16 v[84:87], v[102:105], v[16:19], v[84:87]
	ds_read_b128 v[102:105], v83 offset:6784
	s_waitcnt lgkmcnt(0)
	v_mfma_f32_16x16x32_bf16 v[166:169], v[102:105], v[4:7], v[98:101]
	v_mfma_f32_16x16x32_bf16 v[98:101], v[102:105], v[20:23], v[84:87]
	s_nop 3
	ds_read_b128 v[84:87], v83 offset:9984
	s_waitcnt lgkmcnt(0)
	v_mfma_f32_16x16x32_bf16 v[102:105], v[84:87], v[8:11], 0
	v_mfma_f32_16x16x32_bf16 v[84:87], v[84:87], v[12:15], 0
	v_mfma_f32_16x16x32_bf16 v[102:105], v[144:147], v[0:3], v[102:105]
	v_mfma_f32_16x16x32_bf16 v[84:87], v[144:147], v[16:19], v[84:87]
	ds_read_b128 v[144:147], v83 offset:10112
	v_max_f32_e32 v83, v151, v151
	s_waitcnt lgkmcnt(0)
	v_mfma_f32_16x16x32_bf16 v[176:179], v[144:147], v[4:7], v[102:105]
	v_mfma_f32_16x16x32_bf16 v[102:105], v[144:147], v[20:23], v[84:87]
	v_max_f32_e32 v145, v91, v91
	s_nop 1
	v_max_f32_e32 v84, v150, v150
	v_max_f32_e32 v83, v84, v83
	v_max_f32_e32 v84, v153, v153
	v_max_f32_e32 v85, v152, v152
	v_max_f32_e32 v84, v85, v84
	v_max_f32_e32 v85, v161, v161
	v_max_f32_e32 v86, v160, v160
	v_max_f32_e32 v85, v86, v85
	v_max3_f32 v85, v158, v159, v85
	v_max3_f32 v83, v83, v84, v85
	v_max_f32_e32 v84, v169, v169
	v_max_f32_e32 v85, v168, v168
	v_max_f32_e32 v84, v85, v84
	v_max_f32_e32 v85, v179, v179
	v_max_f32_e32 v86, v178, v178
	v_max_f32_e32 v85, v86, v85
	v_max3_f32 v84, v166, v167, v84
	v_max3_f32 v85, v176, v177, v85
	v_max3_f32 v83, v83, v84, v85
	s_waitcnt lgkmcnt(0)
	v_max_f32_e32 v84, v84, v84
	v_mov_b32_e32 v84, v83
	s_nop 1
	v_permlane16_swap_b32_e32 v83, v84
	v_max_f32_e32 v83, v83, v84
	v_mov_b32_e32 v84, v83
	s_nop 1
	v_permlane32_swap_b32_e32 v83, v84
	v_max3_f32 v174, v82, v83, v84
	v_sub_f32_e32 v82, v82, v174
	v_exp_f32_e32 v146, v82
	v_sub_f32_e32 v82, v150, v174
	v_exp_f32_e32 v142, v82
	v_sub_f32_e32 v82, v151, v174
	v_exp_f32_e32 v144, v82
	v_sub_f32_e32 v82, v152, v174
	v_exp_f32_e32 v150, v82
	v_sub_f32_e32 v82, v153, v174
	v_exp_f32_e32 v152, v82
	v_sub_f32_e32 v82, v158, v174
	v_exp_f32_e32 v156, v82
	v_sub_f32_e32 v82, v159, v174
	v_exp_f32_e32 v158, v82
	v_sub_f32_e32 v82, v160, v174
	v_exp_f32_e32 v160, v82
	v_sub_f32_e32 v82, v161, v174
	v_exp_f32_e32 v162, v82
	v_sub_f32_e32 v82, v166, v174
	v_exp_f32_e32 v164, v82
	v_sub_f32_e32 v82, v167, v174
	v_exp_f32_e32 v166, v82
	v_sub_f32_e32 v82, v168, v174
	v_exp_f32_e32 v168, v82
	v_sub_f32_e32 v82, v169, v174
	v_exp_f32_e32 v170, v82
	v_sub_f32_e32 v82, v176, v174
	v_exp_f32_e32 v172, v82
	v_sub_f32_e32 v82, v177, v174
	v_exp_f32_e32 v176, v82
	v_sub_f32_e32 v82, v178, v174
	v_exp_f32_e32 v178, v82
	v_sub_f32_e32 v82, v179, v174
	v_exp_f32_e32 v180, v82
	v_mul_f32_e32 v84, v68, v146
	v_mul_f32_e32 v85, v69, v146
	v_mul_f32_e32 v82, v66, v146
	v_mul_f32_e32 v83, v67, v146
	v_mul_f32_e32 v88, v72, v146
	v_mul_f32_e32 v89, v73, v146
	v_mul_f32_e32 v86, v70, v146
	v_mul_f32_e32 v87, v71, v146
	v_mul_f32_e32 v76, v76, v146
	v_mul_f32_e32 v77, v77, v146
	v_mul_f32_e32 v74, v74, v146
	v_mul_f32_e32 v75, v75, v146
	v_mul_f32_e32 v68, v80, v146
	v_mul_f32_e32 v69, v81, v146
	v_mul_f32_e32 v66, v78, v146
	v_mul_f32_e32 v67, v79, v146
	v_max_f32_e32 v147, v90, v90
	v_max_f32_e32 v145, v147, v145
	v_max_f32_e32 v147, v93, v93
	v_max_f32_e32 v151, v92, v92
	v_max_f32_e32 v147, v151, v147
	v_max_f32_e32 v151, v97, v97
	v_max_f32_e32 v153, v96, v96
	v_max_f32_e32 v151, v153, v151
	v_max3_f32 v151, v94, v95, v151
	v_max3_f32 v145, v145, v147, v151
	v_max_f32_e32 v147, v101, v101
	v_max_f32_e32 v151, v100, v100
	v_max_f32_e32 v147, v151, v147
	v_max_f32_e32 v151, v105, v105
	v_max_f32_e32 v153, v104, v104
	v_max_f32_e32 v151, v153, v151
	v_max3_f32 v147, v98, v99, v147
	v_max3_f32 v151, v102, v103, v151
	v_max3_f32 v145, v145, v147, v151
	v_cvt_pk_bf16_f32 v70, v142, v144
	v_cvt_pk_bf16_f32 v71, v150, v152
	v_cvt_pk_bf16_f32 v72, v156, v158
	v_cvt_pk_bf16_f32 v73, v160, v162
	s_waitcnt lgkmcnt(0)
	v_max_f32_e32 v147, v147, v147
	v_mov_b32_e32 v147, v145
	s_nop 1
	v_permlane16_swap_b32_e32 v145, v147
	v_max_f32_e32 v145, v145, v147
	v_mov_b32_e32 v147, v145
	s_nop 1
	v_permlane32_swap_b32_e32 v145, v147
	v_max3_f32 v175, v143, v145, v147
	v_sub_f32_e32 v143, v143, v175
	v_sub_f32_e32 v90, v90, v175
	v_exp_f32_e32 v147, v143
	v_exp_f32_e32 v143, v90
	v_sub_f32_e32 v90, v91, v175
	v_exp_f32_e32 v145, v90
	v_sub_f32_e32 v90, v92, v175
	v_exp_f32_e32 v151, v90
	v_sub_f32_e32 v90, v93, v175
	v_exp_f32_e32 v153, v90
	v_sub_f32_e32 v90, v94, v175
	v_exp_f32_e32 v157, v90
	v_sub_f32_e32 v90, v95, v175
	v_exp_f32_e32 v159, v90
	v_add_f32_e32 v90, 0, v142
	v_add_f32_e32 v91, 0, v143
	v_sub_f32_e32 v92, v96, v175
	v_add_f32_e32 v90, v144, v90
	v_add_f32_e32 v91, v145, v91
	v_exp_f32_e32 v161, v92
	v_add_f32_e32 v90, v150, v90
	v_add_f32_e32 v91, v151, v91
	v_sub_f32_e32 v92, v97, v175
	v_add_f32_e32 v90, v152, v90
	v_add_f32_e32 v91, v153, v91
	v_exp_f32_e32 v163, v92
	v_sub_f32_e32 v92, v98, v175
	v_add_f32_e32 v90, v156, v90
	v_add_f32_e32 v91, v157, v91
	v_exp_f32_e32 v165, v92
	v_sub_f32_e32 v92, v99, v175
	v_add_f32_e32 v90, v158, v90
	v_add_f32_e32 v91, v159, v91
	v_exp_f32_e32 v167, v92
	v_sub_f32_e32 v92, v100, v175
	v_exp_f32_e32 v169, v92
	v_sub_f32_e32 v92, v101, v175
	v_add_f32_e32 v90, v160, v90
	v_add_f32_e32 v91, v161, v91
	v_exp_f32_e32 v171, v92
	v_sub_f32_e32 v92, v102, v175
	v_add_f32_e32 v90, v162, v90
	v_add_f32_e32 v91, v163, v91
	v_exp_f32_e32 v173, v92
	v_sub_f32_e32 v92, v103, v175
	v_add_f32_e32 v90, v164, v90
	v_add_f32_e32 v91, v165, v91
	v_exp_f32_e32 v177, v92
	v_sub_f32_e32 v92, v104, v175
	v_add_f32_e32 v90, v166, v90
	v_add_f32_e32 v91, v167, v91
	v_exp_f32_e32 v179, v92
	v_sub_f32_e32 v92, v105, v175
	v_add_f32_e32 v90, v168, v90
	v_add_f32_e32 v91, v169, v91
	v_exp_f32_e32 v181, v92
	v_add_f32_e32 v90, v170, v90
	v_add_f32_e32 v91, v171, v91
	v_mov_b32_e32 v98, v147
	v_add_f32_e32 v90, v172, v90
	v_add_f32_e32 v91, v173, v91
	v_mul_f32_e32 v92, v52, v98
	v_mul_f32_e32 v93, v53, v98
	v_add_f32_e32 v90, v176, v90
	v_add_f32_e32 v91, v177, v91
	v_mul_f32_e32 v96, v56, v98
	v_mul_f32_e32 v97, v57, v98
	v_add_f32_e32 v90, v178, v90
	v_add_f32_e32 v91, v179, v91
	v_mul_f32_e32 v94, v54, v98
	v_mul_f32_e32 v95, v55, v98
	v_add_f32_e32 v90, v180, v90
	v_add_f32_e32 v91, v181, v91
	v_mul_f32_e32 v60, v60, v98
	v_mul_f32_e32 v61, v61, v98
	v_pk_fma_f32 v[140:141], v[140:141], v[146:147], v[90:91]
	v_mul_f32_e32 v90, v50, v98
	v_mul_f32_e32 v91, v51, v98
	v_mul_f32_e32 v58, v58, v98
	v_mul_f32_e32 v59, v59, v98
	v_mul_f32_e32 v52, v64, v98
	v_mul_f32_e32 v53, v65, v98
	v_mul_f32_e32 v50, v62, v98
	v_mul_f32_e32 v51, v63, v98
	ds_read_b64_tr_b16 v[100:101], v127 offset:15872
	ds_read_b64_tr_b16 v[98:99], v127 offset:13312
	ds_read_b64_tr_b16 v[102:103], v127 offset:13320
	v_cvt_pk_bf16_f32 v54, v143, v145
	v_cvt_pk_bf16_f32 v55, v151, v153
	v_cvt_pk_bf16_f32 v56, v157, v159
	v_cvt_pk_bf16_f32 v57, v161, v163
	s_waitcnt lgkmcnt(1)
	v_mfma_f32_16x16x32_bf16 v[82:85], v[98:101], v[70:73], v[82:85]
	ds_read_b64_tr_b16 v[104:105], v127 offset:15880
	v_cvt_pk_bf16_f32 v78, v164, v166
	v_cvt_pk_bf16_f32 v79, v168, v170
	v_mfma_f32_16x16x32_bf16 v[90:93], v[98:101], v[54:57], v[90:93]
	ds_read_b64_tr_b16 v[98:99], v127 offset:13376
	ds_read_b64_tr_b16 v[100:101], v127 offset:15936
	v_cvt_pk_bf16_f32 v80, v172, v176
	v_cvt_pk_bf16_f32 v81, v178, v180
	s_waitcnt lgkmcnt(0)
	v_mfma_f32_16x16x32_bf16 v[74:77], v[98:101], v[70:73], v[74:77]
	v_cvt_pk_bf16_f32 v62, v165, v167
	v_cvt_pk_bf16_f32 v63, v169, v171
	v_cvt_pk_bf16_f32 v64, v173, v177
	v_mfma_f32_16x16x32_bf16 v[58:61], v[98:101], v[54:57], v[58:61]
	ds_read_b64_tr_b16 v[98:99], v127 offset:13384
	ds_read_b64_tr_b16 v[100:101], v127 offset:15944
	v_cvt_pk_bf16_f32 v65, v179, v181
	v_mov_b32_e32 v143, v175
	v_mfma_f32_16x16x32_bf16 v[86:89], v[102:105], v[70:73], v[86:89]
	v_mfma_f32_16x16x32_bf16 v[94:97], v[102:105], v[54:57], v[94:97]
	s_waitcnt lgkmcnt(0)
	v_mfma_f32_16x16x32_bf16 v[102:105], v[98:101], v[70:73], v[66:69]
	v_mfma_f32_16x16x32_bf16 v[98:101], v[98:101], v[54:57], v[50:53]
	s_nop 2
	ds_read_b64_tr_b16 v[50:51], v127 offset:18432
	ds_read_b64_tr_b16 v[52:53], v127 offset:20992
	ds_read_b64_tr_b16 v[54:55], v127 offset:18440
	ds_read_b64_tr_b16 v[56:57], v127 offset:21000
	s_waitcnt lgkmcnt(2)
	v_mfma_f32_16x16x32_bf16 v[66:69], v[50:53], v[78:81], v[82:85]
	s_nop 2
	ds_read_b64_tr_b16 v[82:83], v127 offset:18496
	ds_read_b64_tr_b16 v[84:85], v127 offset:21056
	s_waitcnt lgkmcnt(0)
	v_mfma_f32_16x16x32_bf16 v[74:77], v[82:85], v[78:81], v[74:77]
	v_mfma_f32_16x16x32_bf16 v[58:61], v[82:85], v[62:65], v[58:61]
	ds_read_b64_tr_b16 v[82:83], v127 offset:18504
	ds_read_b64_tr_b16 v[84:85], v127 offset:21064
	v_mfma_f32_16x16x32_bf16 v[50:53], v[50:53], v[62:65], v[90:93]
	v_mfma_f32_16x16x32_bf16 v[70:73], v[54:57], v[78:81], v[86:89]
	v_mfma_f32_16x16x32_bf16 v[54:57], v[54:57], v[62:65], v[94:97]
	s_waitcnt lgkmcnt(0)
	v_mfma_f32_16x16x32_bf16 v[78:81], v[82:85], v[78:81], v[102:105]
	v_mfma_f32_16x16x32_bf16 v[62:65], v[82:85], v[62:65], v[98:101]
	v_mov_b32_e32 v82, v174
	s_branch .LBB0_1064
